# stack + NSA selected loop blocks reordered so the fast path falls into its tail and each tail falls into the other copy's head (two taken branches per step removed)
# speedup vs baseline: 1.0095x; 1.0032x over previous
; DI f32x4 mfma16(bf16x8 a, bf16x8 b, f32x4 c) { return __builtin_amdgcn_mfma_f32_16x16x32_bf16(a, b, c, 0, 0, 0); }
; template <int MODE, bool FX>
; DI void attn_compute(const int lane, const bf16_t* Ks, const bf16_t* Vs, const bf16x8 (&qf)[2][2], AttnSt& st, const float (&invl)[2],
;                      int lo, int hi, float (&impA)[4], float (&impE)[4], const float CL) {
;     ...
;     if (MODE != 0) {
; #pragma unroll
;       for (int c = 0; c < 2; ++c)
;         pf[hh][c] = mk8(pack2(S[2 * c][hh][0], S[2 * c][hh][1]), pack2(S[2 * c][hh][2], S[2 * c][hh][3]),
;                         pack2(S[2 * c + 1][hh][0], S[2 * c + 1][hh][1]), pack2(S[2 * c + 1][hh][2], S[2 * c + 1][hh][3]));
;     }
;   }
;   }
;   if (MODE != 0) {
; #pragma unroll
;     for (int dt = 0; dt < 4; ++dt) {
;       const int row = dt * 16 + col;
;       const int sw = (row >> 1) & 7;
; #pragma unroll
;       for (int c = 0; c < 2; ++c) {
;         uint2 a = *(const uint2*)(Vs + row * 64 + (((4 * c + (quad >> 1)) ^ sw) << 3) + (quad & 1) * 4);
;         uint2 b = *(const uint2*)(Vs + row * 64 + (((4 * c + 2 + (quad >> 1)) ^ sw) << 3) + (quad & 1) * 4);
;         bf16x8 vf = mk8(a.x, a.y, b.x, b.y);
; #pragma unroll
;         for (int hh = 0; hh < 2; ++hh) st.O[hh][dt] = mfma16(vf, pf[hh][c], st.O[hh][dt]);
;       }
;     }
;     if (FX && MODE == 2) {
;       const bf16x8 ones = mk8(0x3F803F80u, 0x3F803F80u, 0x3F803F80u, 0x3F803F80u);
; #pragma unroll
;       for (int c = 0; c < 2; ++c)
; #pragma unroll
;         for (int hh = 0; hh < 2; ++hh) st.L[hh] = mfma16(ones, pf[hh][c], st.L[hh]);
;     }
.LBB0_666_p1:
	v_cvt_pk_bf16_f32 v82, v164, v165
	v_cvt_pk_bf16_f32 v83, v166, v167
	v_cvt_pk_bf16_f32 v84, v168, v169
	v_cvt_pk_bf16_f32 v85, v170, v171
	v_cvt_pk_bf16_f32 v86, v172, v173
	v_cvt_pk_bf16_f32 v87, v174, v175
	v_cvt_pk_bf16_f32 v88, v176, v177
	v_cvt_pk_bf16_f32 v89, v178, v179
	s_mov_b32 s10, s8
	s_mov_b32 s11, s8
	s_mov_b32 s9, s8
	v_mov_b64_e32 v[92:93], s[10:11]
	v_mov_b64_e32 v[90:91], s[8:9]
	s_waitcnt lgkmcnt(0)
	v_mfma_f32_16x16x32_bf16 v[50:53], v[220:223], v[74:77], v[50:53]
	v_mfma_f32_16x16x32_bf16 v[30:33], v[220:223], v[82:85], v[30:33]
	v_mfma_f32_16x16x32_bf16 v[42:45], v[228:231], v[74:77], v[42:45]
	v_mfma_f32_16x16x32_bf16 v[26:29], v[228:231], v[82:85], v[26:29]
	v_mfma_f32_16x16x32_bf16 v[38:41], v[236:239], v[74:77], v[38:41]
	v_mfma_f32_16x16x32_bf16 v[22:25], v[236:239], v[82:85], v[22:25]
	v_mfma_f32_16x16x32_bf16 v[34:37], v[244:247], v[74:77], v[34:37]
	v_mfma_f32_16x16x32_bf16 v[18:21], v[244:247], v[82:85], v[18:21]
	v_mfma_f32_16x16x32_bf16 v[54:57], v[90:93], v[74:77], v[54:57]
	v_mfma_f32_16x16x32_bf16 v[46:49], v[90:93], v[82:85], v[46:49]
	v_mfma_f32_16x16x32_bf16 v[50:53], v[224:227], v[78:81], v[50:53]
	v_mfma_f32_16x16x32_bf16 v[30:33], v[224:227], v[86:89], v[30:33]
	v_mfma_f32_16x16x32_bf16 v[42:45], v[232:235], v[78:81], v[42:45]
	v_mfma_f32_16x16x32_bf16 v[26:29], v[232:235], v[86:89], v[26:29]
	v_mfma_f32_16x16x32_bf16 v[38:41], v[240:243], v[78:81], v[38:41]
	v_mfma_f32_16x16x32_bf16 v[22:25], v[240:243], v[86:89], v[22:25]
	v_mfma_f32_16x16x32_bf16 v[34:37], v[198:201], v[78:81], v[34:37]
	v_mfma_f32_16x16x32_bf16 v[18:21], v[198:201], v[86:89], v[18:21]
	v_mfma_f32_16x16x32_bf16 v[54:57], v[90:93], v[78:81], v[54:57]
	v_mfma_f32_16x16x32_bf16 v[46:49], v[90:93], v[86:89], v[46:49]
	s_branch .LBB0_667_p1
; template <int MODE, bool FX>
; DI void attn_compute(const int lane, const bf16_t* Ks, const bf16_t* Vs, const bf16x8 (&qf)[2][2], AttnSt& st, const float (&invl)[2],
;                      int lo, int hi, float (&impA)[4], float (&impE)[4], const float CL) {
;     ...
;   for (int ks = 0; ks < 2; ++ks) {
; #pragma unroll
;     for (int kt = 0; kt < 4; ++kt) {
;       int row = kt * 16 + col;
;       bf16x8 kf = *(const bf16x8*)(Ks + row * 64 + (((ks * 4 + quad) ^ ((row >> 1) & 7)) << 3));
; #pragma unroll
;       for (int hh = 0; hh < 2; ++hh) S[kt][hh] = mfma16(kf, qf[hh][ks], S[kt][hh]);
;     }
;   }
;   bf16x8 pf[2][2];
;   const bool full = (lo <= 0) && (hi >= 63);
;   const bool none = (hi < 0) || (lo > 63) || (hi < lo);
;   if (__all(full || none)) {
;     constexpr float L2E = 1.4426950408889634f;
; #pragma unroll
;     for (int hh = 0; hh < 2; ++hh) {
;       float mL;
;       float il = 1.f;
;       if (FX) {
;         mL = full ? CL : 1e30f;
;         if (MODE == 1) il = invl[hh];
;       } else if (MODE != 1) {
;         float mx = -1e30f;
; #pragma unroll
;         for (int kt = 0; kt < 4; ++kt)
; #pragma unroll
;           for (int j = 0; j < 4; ++j) mx = fmaxf(mx, S[kt][hh][j]);
;         mx = full ? mx : -1e30f;
;         mx = fmaxf(mx, shx(mx, 16, lane));
;         mx = fmaxf(mx, shx(mx, 32, lane));
;         const float m_new = fmaxf(st.m[hh], mx);
;         const float alpha = __expf(st.m[hh] - m_new);
;         st.m[hh] = m_new;
;         st.l[hh] *= alpha;
;         if (MODE == 2) {
; #pragma unroll
;           for (int dt = 0; dt < 4; ++dt) st.O[hh][dt] *= alpha;
;         }
;         mL = full ? m_new * L2E : 1e30f;
;       } else {
;         mL = full ? st.m[hh] * L2E : 1e30f;
;         il = invl[hh];
;       }
;       float rs = 0.f;
; #pragma unroll
;       for (int kt = 0; kt < 4; ++kt) {
;         float a = 0.f;
; #pragma unroll
;         for (int j = 0; j < 4; ++j) {
;           float pv = __builtin_amdgcn_exp2f(fmaf(S[kt][hh][j], L2E, -mL));
;           if (MODE == 1) pv *= il;
;           S[kt][hh][j] = pv;
;           a += pv;
;         }
; template <bool FX>
; DI void nsa_tile(const Params& p, int b, int g, int tile, bf16_t* lds, const float CL) {
;     ...
;       for (int s = 0; s <= cur; ++s) {
;         __syncthreads();
;         tile64_sstore(tid, Ks, rk0, rk1);
;         tile64_sstore(tid, Vs, rv0, rv1);
;         __syncthreads();
.Lnsa_fast_p1:
	s_waitcnt lgkmcnt(7)
	v_mfma_f32_16x16x32_bf16 v[98:101], v[220:223], v[2:5], 0
	s_waitcnt lgkmcnt(6)
	v_mfma_f32_16x16x32_bf16 v[106:109], v[224:227], v[2:5], 0
	s_waitcnt lgkmcnt(5)
	v_mfma_f32_16x16x32_bf16 v[102:105], v[228:231], v[2:5], 0
	s_waitcnt lgkmcnt(4)
	v_mfma_f32_16x16x32_bf16 v[110:113], v[232:235], v[2:5], 0
	s_waitcnt lgkmcnt(3)
	v_mfma_f32_16x16x32_bf16 v[98:101], v[236:239], v[6:9], v[98:101]
	s_waitcnt lgkmcnt(2)
	v_mfma_f32_16x16x32_bf16 v[106:109], v[240:243], v[6:9], v[106:109]
	s_waitcnt lgkmcnt(1)
	v_mfma_f32_16x16x32_bf16 v[102:105], v[244:247], v[6:9], v[102:105]
	s_waitcnt lgkmcnt(0)
	v_mfma_f32_16x16x32_bf16 v[110:113], v[198:201], v[6:9], v[110:113]
	v_mfma_f32_16x16x32_bf16 v[90:93], v[220:223], v[10:13], 0
	v_mfma_f32_16x16x32_bf16 v[94:97], v[224:227], v[10:13], 0
	v_mfma_f32_16x16x32_bf16 v[82:85], v[228:231], v[10:13], 0
	v_mfma_f32_16x16x32_bf16 v[86:89], v[232:235], v[10:13], 0
	v_fmamk_f32 v74, v98, 0x3fb8aa3b, v217
	v_fmamk_f32 v75, v99, 0x3fb8aa3b, v217
	v_mfma_f32_16x16x32_bf16 v[90:93], v[236:239], v[14:17], v[90:93]
	v_fmamk_f32 v76, v100, 0x3fb8aa3b, v217
	v_fmamk_f32 v77, v101, 0x3fb8aa3b, v217
	v_mfma_f32_16x16x32_bf16 v[94:97], v[240:243], v[14:17], v[94:97]
	v_fmamk_f32 v78, v106, 0x3fb8aa3b, v217
	v_fmamk_f32 v79, v107, 0x3fb8aa3b, v217
	v_mfma_f32_16x16x32_bf16 v[82:85], v[244:247], v[14:17], v[82:85]
	v_fmamk_f32 v80, v108, 0x3fb8aa3b, v217
	v_fmamk_f32 v81, v109, 0x3fb8aa3b, v217
	v_mfma_f32_16x16x32_bf16 v[86:89], v[198:201], v[14:17], v[86:89]
	ds_read_b64 v[220:221], v207 offset:57344
	v_fmamk_f32 v164, v102, 0x3fb8aa3b, v217
	ds_read_b64 v[222:223], v208 offset:57344
	v_fmamk_f32 v165, v103, 0x3fb8aa3b, v217
	ds_read_b64 v[224:225], v209 offset:57344
	v_fmamk_f32 v166, v104, 0x3fb8aa3b, v217
	ds_read_b64 v[226:227], v210 offset:57344
	v_fmamk_f32 v167, v105, 0x3fb8aa3b, v217
	ds_read_b64 v[228:229], v207 offset:59392
	v_fmamk_f32 v168, v110, 0x3fb8aa3b, v217
	ds_read_b64 v[230:231], v208 offset:59392
	v_fmamk_f32 v169, v111, 0x3fb8aa3b, v217
	ds_read_b64 v[232:233], v209 offset:59392
	v_fmamk_f32 v170, v112, 0x3fb8aa3b, v217
	ds_read_b64 v[234:235], v210 offset:59392
	v_fmamk_f32 v171, v113, 0x3fb8aa3b, v217
	ds_read_b64 v[236:237], v207 offset:61440
	v_exp_f32_e32 v74, v74
	ds_read_b64 v[238:239], v208 offset:61440
	v_exp_f32_e32 v75, v75
	ds_read_b64 v[240:241], v209 offset:61440
	v_exp_f32_e32 v76, v76
	ds_read_b64 v[242:243], v210 offset:61440
	v_exp_f32_e32 v77, v77
	ds_read_b64 v[244:245], v211 offset:57344
	v_exp_f32_e32 v78, v78
	ds_read_b64 v[246:247], v212 offset:57344
	v_exp_f32_e32 v79, v79
	ds_read_b64 v[198:199], v213 offset:57344
	v_exp_f32_e32 v80, v80
	ds_read_b64 v[200:201], v214 offset:57344
	v_exp_f32_e32 v81, v81
	v_exp_f32_e32 v164, v164
	v_exp_f32_e32 v165, v165
	v_exp_f32_e32 v166, v166
	v_exp_f32_e32 v167, v167
	v_exp_f32_e32 v168, v168
	v_exp_f32_e32 v169, v169
	v_exp_f32_e32 v170, v170
	v_exp_f32_e32 v171, v171
	v_cvt_pk_bf16_f32 v74, v74, v75
	v_cvt_pk_bf16_f32 v75, v76, v77
	v_cvt_pk_bf16_f32 v76, v78, v79
	v_cvt_pk_bf16_f32 v77, v80, v81
	v_cvt_pk_bf16_f32 v78, v164, v165
	v_cvt_pk_bf16_f32 v79, v166, v167
	v_cvt_pk_bf16_f32 v80, v168, v169
	v_cvt_pk_bf16_f32 v81, v170, v171
	s_waitcnt lgkmcnt(0)
	v_fmamk_f32 v164, v90, 0x3fb8aa3b, v217
	v_fmamk_f32 v165, v91, 0x3fb8aa3b, v217
	v_fmamk_f32 v166, v92, 0x3fb8aa3b, v217
	v_mfma_f32_16x16x32_bf16 v[50:53], v[220:223], v[74:77], v[50:53]
	v_fmamk_f32 v167, v93, 0x3fb8aa3b, v217
	v_mfma_f32_16x16x32_bf16 v[42:45], v[228:231], v[74:77], v[42:45]
	v_fmamk_f32 v168, v94, 0x3fb8aa3b, v217
	v_fmamk_f32 v169, v95, 0x3fb8aa3b, v217
	v_mfma_f32_16x16x32_bf16 v[38:41], v[236:239], v[74:77], v[38:41]
	v_fmamk_f32 v170, v96, 0x3fb8aa3b, v217
	v_fmamk_f32 v171, v97, 0x3fb8aa3b, v217
	v_fmamk_f32 v172, v82, 0x3fb8aa3b, v217
	v_fmamk_f32 v173, v83, 0x3fb8aa3b, v217
	v_mfma_f32_16x16x32_bf16 v[34:37], v[244:247], v[74:77], v[34:37]
	v_fmamk_f32 v174, v84, 0x3fb8aa3b, v217
	v_fmamk_f32 v175, v85, 0x3fb8aa3b, v217
	v_fmamk_f32 v176, v86, 0x3fb8aa3b, v217
	v_fmamk_f32 v177, v87, 0x3fb8aa3b, v217
	v_mfma_f32_16x16x32_bf16 v[50:53], v[224:227], v[78:81], v[50:53]
	v_fmamk_f32 v178, v88, 0x3fb8aa3b, v217
	v_fmamk_f32 v179, v89, 0x3fb8aa3b, v217
	v_exp_f32_e32 v164, v164
	v_exp_f32_e32 v165, v165
	v_mfma_f32_16x16x32_bf16 v[42:45], v[232:235], v[78:81], v[42:45]
	v_exp_f32_e32 v166, v166
	v_exp_f32_e32 v167, v167
	v_exp_f32_e32 v168, v168
	v_exp_f32_e32 v169, v169
	v_mfma_f32_16x16x32_bf16 v[38:41], v[240:243], v[78:81], v[38:41]
	v_exp_f32_e32 v170, v170
	v_exp_f32_e32 v171, v171
	v_exp_f32_e32 v172, v172
	v_exp_f32_e32 v173, v173
	v_mfma_f32_16x16x32_bf16 v[34:37], v[198:201], v[78:81], v[34:37]
	v_exp_f32_e32 v174, v174
	v_exp_f32_e32 v175, v175
	v_exp_f32_e32 v176, v176
	v_exp_f32_e32 v177, v177
	v_mfma_f32_16x16x32_bf16 v[54:57], v[58:61], v[74:77], v[54:57]
	v_exp_f32_e32 v178, v178
	v_exp_f32_e32 v179, v179
	v_cvt_pk_bf16_f32 v82, v164, v165
	v_cvt_pk_bf16_f32 v83, v166, v167
	v_mfma_f32_16x16x32_bf16 v[54:57], v[58:61], v[78:81], v[54:57]
	v_cvt_pk_bf16_f32 v84, v168, v169
	v_cvt_pk_bf16_f32 v85, v170, v171
	v_cvt_pk_bf16_f32 v86, v172, v173
	v_cvt_pk_bf16_f32 v87, v174, v175
	v_cvt_pk_bf16_f32 v88, v176, v177
	v_cvt_pk_bf16_f32 v89, v178, v179
	s_nop 1
	v_mfma_f32_16x16x32_bf16 v[30:33], v[220:223], v[82:85], v[30:33]
	v_mfma_f32_16x16x32_bf16 v[26:29], v[228:231], v[82:85], v[26:29]
	v_mfma_f32_16x16x32_bf16 v[22:25], v[236:239], v[82:85], v[22:25]
	v_mfma_f32_16x16x32_bf16 v[18:21], v[244:247], v[82:85], v[18:21]
	v_mfma_f32_16x16x32_bf16 v[30:33], v[224:227], v[86:89], v[30:33]
	v_mfma_f32_16x16x32_bf16 v[26:29], v[232:235], v[86:89], v[26:29]
	v_mfma_f32_16x16x32_bf16 v[22:25], v[240:243], v[86:89], v[22:25]
	v_mfma_f32_16x16x32_bf16 v[18:21], v[198:201], v[86:89], v[18:21]
	v_mfma_f32_16x16x32_bf16 v[46:49], v[58:61], v[82:85], v[46:49]
	v_mfma_f32_16x16x32_bf16 v[46:49], v[58:61], v[86:89], v[46:49]
.LBB0_667_p1:
	s_add_i32 s28, s28, 64
	s_cmp_eq_u32 s25, s68
	v_subrev_u32_e32 v187, 64, v187
	s_cbranch_scc1 .LBB0_675
.LBB0_668:
	s_add_i32 s68, s68, 1
	s_and_b32 s87, s68, 31
	s_cmp_lg_u32 s87, 0
	s_cbranch_scc1 .Lnsa_mk
	s_cmp_lt_u32 s68, 32
	s_cselect_b64 vcc, -1, 0
	s_cmp_lt_u32 s68, 64
	s_cselect_b64 s[2:3], -1, 0
	s_cmpk_lt_u32 s68, 0x60
	s_cselect_b64 s[4:5], -1, 0
	v_cndmask_b32_e64 v72, v183, v182, s[4:5]
	v_cndmask_b32_e64 v72, v72, v181, s[2:3]
	v_cndmask_b32_e32 v72, v72, v180, vcc

; template <int MODE, bool FX>
; DI void attn_compute(const int lane, const bf16_t* Ks, const bf16_t* Vs, const bf16x8 (&qf)[2][2], AttnSt& st, const float (&invl)[2],
;                      int lo, int hi, float (&impA)[4], float (&impE)[4], const float CL) {
;     ...
;   for (int ks = 0; ks < 2; ++ks) {
; #pragma unroll
;     for (int kt = 0; kt < 4; ++kt) {
;       int row = kt * 16 + col;
;       bf16x8 kf = *(const bf16x8*)(Ks + row * 64 + (((ks * 4 + quad) ^ ((row >> 1) & 7)) << 3));
; #pragma unroll
;       for (int hh = 0; hh < 2; ++hh) S[kt][hh] = mfma16(kf, qf[hh][ks], S[kt][hh]);
;     }
;   }
;   bf16x8 pf[2][2];
;   const bool full = (lo <= 0) && (hi >= 63);
;   const bool none = (hi < 0) || (lo > 63) || (hi < lo);
;   if (__all(full || none)) {
;     constexpr float L2E = 1.4426950408889634f;
; #pragma unroll
;     for (int hh = 0; hh < 2; ++hh) {
;       float mL;
;       float il = 1.f;
;       if (FX) {
;         mL = full ? CL : 1e30f;
;         if (MODE == 1) il = invl[hh];
;       } else if (MODE != 1) {
;         float mx = -1e30f;
; #pragma unroll
;         for (int kt = 0; kt < 4; ++kt)
; #pragma unroll
;           for (int j = 0; j < 4; ++j) mx = fmaxf(mx, S[kt][hh][j]);
;         mx = full ? mx : -1e30f;
;         mx = fmaxf(mx, shx(mx, 16, lane));
;         mx = fmaxf(mx, shx(mx, 32, lane));
;         const float m_new = fmaxf(st.m[hh], mx);
;         const float alpha = __expf(st.m[hh] - m_new);
;         st.m[hh] = m_new;
;         st.l[hh] *= alpha;
;         if (MODE == 2) {
; #pragma unroll
;           for (int dt = 0; dt < 4; ++dt) st.O[hh][dt] *= alpha;
;         }
;         mL = full ? m_new * L2E : 1e30f;
;       } else {
;         mL = full ? st.m[hh] * L2E : 1e30f;
;         il = invl[hh];
;       }
;       float rs = 0.f;
; #pragma unroll
;       for (int kt = 0; kt < 4; ++kt) {
;         float a = 0.f;
; #pragma unroll
;         for (int j = 0; j < 4; ++j) {
;           float pv = __builtin_amdgcn_exp2f(fmaf(S[kt][hh][j], L2E, -mL));
;           if (MODE == 1) pv *= il;
;           S[kt][hh][j] = pv;
;           a += pv;
;         }
; template <bool FX>
; DI void nsa_tile(const Params& p, int b, int g, int tile, bf16_t* lds, const float CL) {
;     ...
;       for (int s = 0; s <= cur; ++s) {
;         __syncthreads();
;         tile64_sstore(tid, Ks, rk0, rk1);
;         tile64_sstore(tid, Vs, rv0, rv1);
;         __syncthreads();
.Lnsa_fast:
	s_waitcnt lgkmcnt(7)
	v_mfma_f32_16x16x32_bf16 v[98:101], v[220:223], v[2:5], 0
	s_waitcnt lgkmcnt(6)
	v_mfma_f32_16x16x32_bf16 v[106:109], v[224:227], v[2:5], 0
	s_waitcnt lgkmcnt(5)
	v_mfma_f32_16x16x32_bf16 v[102:105], v[228:231], v[2:5], 0
	s_waitcnt lgkmcnt(4)
	v_mfma_f32_16x16x32_bf16 v[110:113], v[232:235], v[2:5], 0
	s_waitcnt lgkmcnt(3)
	v_mfma_f32_16x16x32_bf16 v[98:101], v[236:239], v[6:9], v[98:101]
	s_waitcnt lgkmcnt(2)
	v_mfma_f32_16x16x32_bf16 v[106:109], v[240:243], v[6:9], v[106:109]
	s_waitcnt lgkmcnt(1)
	v_mfma_f32_16x16x32_bf16 v[102:105], v[244:247], v[6:9], v[102:105]
	s_waitcnt lgkmcnt(0)
	v_mfma_f32_16x16x32_bf16 v[110:113], v[198:201], v[6:9], v[110:113]
	v_mfma_f32_16x16x32_bf16 v[90:93], v[220:223], v[10:13], 0
	v_mfma_f32_16x16x32_bf16 v[94:97], v[224:227], v[10:13], 0
	v_mfma_f32_16x16x32_bf16 v[82:85], v[228:231], v[10:13], 0
	v_mfma_f32_16x16x32_bf16 v[86:89], v[232:235], v[10:13], 0
	v_fmamk_f32 v74, v98, 0x3fb8aa3b, v217
	v_fmamk_f32 v75, v99, 0x3fb8aa3b, v217
	v_mfma_f32_16x16x32_bf16 v[90:93], v[236:239], v[14:17], v[90:93]
	v_fmamk_f32 v76, v100, 0x3fb8aa3b, v217
	v_fmamk_f32 v77, v101, 0x3fb8aa3b, v217
	v_mfma_f32_16x16x32_bf16 v[94:97], v[240:243], v[14:17], v[94:97]
	v_fmamk_f32 v78, v106, 0x3fb8aa3b, v217
	v_fmamk_f32 v79, v107, 0x3fb8aa3b, v217
	v_mfma_f32_16x16x32_bf16 v[82:85], v[244:247], v[14:17], v[82:85]
	v_fmamk_f32 v80, v108, 0x3fb8aa3b, v217
	v_fmamk_f32 v81, v109, 0x3fb8aa3b, v217
	v_mfma_f32_16x16x32_bf16 v[86:89], v[198:201], v[14:17], v[86:89]
	ds_read_b64 v[220:221], v207 offset:8192
	v_fmamk_f32 v164, v102, 0x3fb8aa3b, v217
	ds_read_b64 v[222:223], v208 offset:8192
	v_fmamk_f32 v165, v103, 0x3fb8aa3b, v217
	ds_read_b64 v[224:225], v209 offset:8192
	v_fmamk_f32 v166, v104, 0x3fb8aa3b, v217
	ds_read_b64 v[226:227], v210 offset:8192
	v_fmamk_f32 v167, v105, 0x3fb8aa3b, v217
	ds_read_b64 v[228:229], v207 offset:10240
	v_fmamk_f32 v168, v110, 0x3fb8aa3b, v217
	ds_read_b64 v[230:231], v208 offset:10240
	v_fmamk_f32 v169, v111, 0x3fb8aa3b, v217
	ds_read_b64 v[232:233], v209 offset:10240
	v_fmamk_f32 v170, v112, 0x3fb8aa3b, v217
	ds_read_b64 v[234:235], v210 offset:10240
	v_fmamk_f32 v171, v113, 0x3fb8aa3b, v217
	ds_read_b64 v[236:237], v207 offset:12288
	v_exp_f32_e32 v74, v74
	ds_read_b64 v[238:239], v208 offset:12288
	v_exp_f32_e32 v75, v75
	ds_read_b64 v[240:241], v209 offset:12288
	v_exp_f32_e32 v76, v76
	ds_read_b64 v[242:243], v210 offset:12288
	v_exp_f32_e32 v77, v77
	ds_read_b64 v[244:245], v211 offset:8192
	v_exp_f32_e32 v78, v78
	ds_read_b64 v[246:247], v212 offset:8192
	v_exp_f32_e32 v79, v79
	ds_read_b64 v[198:199], v213 offset:8192
	v_exp_f32_e32 v80, v80
	ds_read_b64 v[200:201], v214 offset:8192
	v_exp_f32_e32 v81, v81
	v_exp_f32_e32 v164, v164
	v_exp_f32_e32 v165, v165
	v_exp_f32_e32 v166, v166
	v_exp_f32_e32 v167, v167
	v_exp_f32_e32 v168, v168
	v_exp_f32_e32 v169, v169
	v_exp_f32_e32 v170, v170
	v_exp_f32_e32 v171, v171
	v_cvt_pk_bf16_f32 v74, v74, v75
	v_cvt_pk_bf16_f32 v75, v76, v77
	v_cvt_pk_bf16_f32 v76, v78, v79
	v_cvt_pk_bf16_f32 v77, v80, v81
	v_cvt_pk_bf16_f32 v78, v164, v165
	v_cvt_pk_bf16_f32 v79, v166, v167
	v_cvt_pk_bf16_f32 v80, v168, v169
	v_cvt_pk_bf16_f32 v81, v170, v171
	s_waitcnt lgkmcnt(0)
	v_fmamk_f32 v164, v90, 0x3fb8aa3b, v217
	v_fmamk_f32 v165, v91, 0x3fb8aa3b, v217
	v_fmamk_f32 v166, v92, 0x3fb8aa3b, v217
	v_mfma_f32_16x16x32_bf16 v[50:53], v[220:223], v[74:77], v[50:53]
	v_fmamk_f32 v167, v93, 0x3fb8aa3b, v217
	v_mfma_f32_16x16x32_bf16 v[42:45], v[228:231], v[74:77], v[42:45]
	v_fmamk_f32 v168, v94, 0x3fb8aa3b, v217
	v_fmamk_f32 v169, v95, 0x3fb8aa3b, v217
	v_mfma_f32_16x16x32_bf16 v[38:41], v[236:239], v[74:77], v[38:41]
	v_fmamk_f32 v170, v96, 0x3fb8aa3b, v217
	v_fmamk_f32 v171, v97, 0x3fb8aa3b, v217
	v_fmamk_f32 v172, v82, 0x3fb8aa3b, v217
	v_fmamk_f32 v173, v83, 0x3fb8aa3b, v217
	v_mfma_f32_16x16x32_bf16 v[34:37], v[244:247], v[74:77], v[34:37]
	v_fmamk_f32 v174, v84, 0x3fb8aa3b, v217
	v_fmamk_f32 v175, v85, 0x3fb8aa3b, v217
	v_fmamk_f32 v176, v86, 0x3fb8aa3b, v217
	v_fmamk_f32 v177, v87, 0x3fb8aa3b, v217
	v_mfma_f32_16x16x32_bf16 v[50:53], v[224:227], v[78:81], v[50:53]
	v_fmamk_f32 v178, v88, 0x3fb8aa3b, v217
	v_fmamk_f32 v179, v89, 0x3fb8aa3b, v217
	v_exp_f32_e32 v164, v164
	v_exp_f32_e32 v165, v165
	v_mfma_f32_16x16x32_bf16 v[42:45], v[232:235], v[78:81], v[42:45]
	v_exp_f32_e32 v166, v166
	v_exp_f32_e32 v167, v167
	v_exp_f32_e32 v168, v168
	v_exp_f32_e32 v169, v169
	v_mfma_f32_16x16x32_bf16 v[38:41], v[240:243], v[78:81], v[38:41]
	v_exp_f32_e32 v170, v170
	v_exp_f32_e32 v171, v171
	v_exp_f32_e32 v172, v172
	v_exp_f32_e32 v173, v173
	v_mfma_f32_16x16x32_bf16 v[34:37], v[198:201], v[78:81], v[34:37]
	v_exp_f32_e32 v174, v174
	v_exp_f32_e32 v175, v175
	v_exp_f32_e32 v176, v176
	v_exp_f32_e32 v177, v177
	v_mfma_f32_16x16x32_bf16 v[54:57], v[58:61], v[74:77], v[54:57]
	v_exp_f32_e32 v178, v178
	v_exp_f32_e32 v179, v179
	v_cvt_pk_bf16_f32 v82, v164, v165
	v_cvt_pk_bf16_f32 v83, v166, v167
	v_mfma_f32_16x16x32_bf16 v[54:57], v[58:61], v[78:81], v[54:57]
	v_cvt_pk_bf16_f32 v84, v168, v169
	v_cvt_pk_bf16_f32 v85, v170, v171
	v_cvt_pk_bf16_f32 v86, v172, v173
	v_cvt_pk_bf16_f32 v87, v174, v175
	v_cvt_pk_bf16_f32 v88, v176, v177
	v_cvt_pk_bf16_f32 v89, v178, v179
	s_nop 1
	v_mfma_f32_16x16x32_bf16 v[30:33], v[220:223], v[82:85], v[30:33]
	v_mfma_f32_16x16x32_bf16 v[26:29], v[228:231], v[82:85], v[26:29]
	v_mfma_f32_16x16x32_bf16 v[22:25], v[236:239], v[82:85], v[22:25]
	v_mfma_f32_16x16x32_bf16 v[18:21], v[244:247], v[82:85], v[18:21]
	v_mfma_f32_16x16x32_bf16 v[30:33], v[224:227], v[86:89], v[30:33]
	v_mfma_f32_16x16x32_bf16 v[26:29], v[232:235], v[86:89], v[26:29]
	v_mfma_f32_16x16x32_bf16 v[22:25], v[240:243], v[86:89], v[22:25]
	v_mfma_f32_16x16x32_bf16 v[18:21], v[198:201], v[86:89], v[18:21]
	v_mfma_f32_16x16x32_bf16 v[46:49], v[58:61], v[82:85], v[46:49]
	v_mfma_f32_16x16x32_bf16 v[46:49], v[58:61], v[86:89], v[46:49]
.LBB0_667:
	s_add_i32 s28, s28, 64
	s_cmp_eq_u32 s25, s68
	v_subrev_u32_e32 v187, 64, v187
	s_cbranch_scc1 .LBB0_675
.LBB0_668_p1:
	s_add_i32 s68, s68, 1
	s_and_b32 s87, s68, 31
	s_cmp_lg_u32 s87, 0
	s_cbranch_scc1 .Lnsa_mk_p1
	s_cmp_lt_u32 s68, 32
	s_cselect_b64 vcc, -1, 0
	s_cmp_lt_u32 s68, 64
	s_cselect_b64 s[2:3], -1, 0
	s_cmpk_lt_u32 s68, 0x60
	s_cselect_b64 s[4:5], -1, 0
	v_cndmask_b32_e64 v72, v183, v182, s[4:5]
	v_cndmask_b32_e64 v72, v72, v181, s[2:3]
	v_cndmask_b32_e32 v72, v72, v180, vcc
